# G0 K loop: LDS-DMA for k-tile kt+3 issued right behind the k-step barrier (half a k-step more time in flight)
# baseline (speedup 1.0000x reference)
; #define WAIT_V(n) asm volatile("s_waitcnt vmcnt(" #n ")" ::: "memory")
; #define BAR __builtin_amdgcn_s_barrier()
; #define LDA_(dst, ai) _Pragma("unroll") for (int m = 0; m < 4; ++m) dst[m] = *(const bf16x8*)(sb + (ai) * 8192 + la0 + m * 1024)
; #define LDB_(dst) _Pragma("unroll") for (int bj = 0; bj < 2; ++bj) _Pragma("unroll") for (int n = 0; n < 2; ++n) dst[bj][n] = *(const bf16x8*)(sb + 16384 + bj * 8192 + lb0 + n * 1024)
; #define MMA_(ai, bf_, af_) _Pragma("unroll") for (int bj = 0; bj < 2; ++bj) _Pragma("unroll") for (int m = 0; m < 4; ++m) _Pragma("unroll") for (int n = 0; n < 2; ++n) \
;         acc[ai][bj][m][n] = __builtin_amdgcn_mfma_f32_16x16x32_bf16(bf_[bj][n], af_[m], acc[ai][bj][m][n], 0, 0, 0)
; template <int MODE>
; DI void gemm_phase(const Params& p, int layer, int hf, unsigned char* shmc, int tid) {
;     ...
;     for (int kt = 0; kt < nt; ++kt) {
;       const int rem = nt - 1 - kt;
;       if (rem >= 2) WAIT_V(8); else if (rem == 1) WAIT_V(4); else WAIT_V(0);
;       BAR;
;       const unsigned char* sb = shmc + (kt & 3) * 32768;
;     ...
;       {
;         bf16x8 b0[2][2], a0[4], a1[4];
;         LDB_(b0); LDA_(a0, 0);
;         __builtin_amdgcn_sched_barrier(0);
;         LDA_(a1, 1); MMA_(0, b0, a0);
;         __builtin_amdgcn_sched_barrier(0);
;         if (kt + 3 < nt) STAGE_ALL((kt + 3) & 3, kt + 3);
;         __builtin_amdgcn_sched_barrier(0);
;         MMA_(1, b0, a1);
;       }
.Lg0_loop:
	s_waitcnt vmcnt(4)
	s_barrier
	s_add_u32 m0, s29, 0x18000
	s_add_u32 s18, s98, 0x40000
	s_addc_u32 s19, s99, 0
	global_load_lds_dwordx4 v160, s[98:99]
	s_add_u32 m0, s29, 0x1c000
	s_add_u32 s16, s100, 0x40000
	s_addc_u32 s17, s101, 0
	global_load_lds_dwordx4 v160, s[100:101]
	s_add_u32 m0, s29, 0x1a000
	s_add_u32 s98, s98, 0x2000
	s_addc_u32 s99, s99, 0
	global_load_lds_dwordx4 v160, s[18:19]
	s_add_u32 m0, s29, 0x1e000
	s_add_u32 s100, s100, 0x2000
	s_addc_u32 s101, s101, 0
	global_load_lds_dwordx4 v160, s[16:17]
	ds_read_b128 v[156:159], v191 offset:8192
	ds_read_b128 v[240:243], v191 offset:9216
	ds_read_b128 v[244:247], v191 offset:10240
	ds_read_b128 v[248:251], v191 offset:11264
	s_waitcnt lgkmcnt(4)
	v_mfma_f32_16x16x32_bf16 v[124:127], v[140:143], v[132:135], v[124:127]
	v_mfma_f32_16x16x32_bf16 v[120:123], v[144:147], v[132:135], v[120:123]
	ds_read_b128 v[208:211], v194 offset:49152
	v_mfma_f32_16x16x32_bf16 v[116:119], v[140:143], v[148:151], v[116:119]
	v_mfma_f32_16x16x32_bf16 v[108:111], v[144:147], v[148:151], v[108:111]
	ds_read_b128 v[212:215], v194 offset:50176
	v_mfma_f32_16x16x32_bf16 v[100:103], v[140:143], v[152:155], v[100:103]
	v_mfma_f32_16x16x32_bf16 v[92:95], v[144:147], v[152:155], v[92:95]
	ds_read_b128 v[216:219], v194 offset:57344
	v_mfma_f32_16x16x32_bf16 v[112:115], v[136:139], v[132:135], v[112:115]
	v_mfma_f32_16x16x32_bf16 v[104:107], v[128:131], v[132:135], v[104:107]
	ds_read_b128 v[220:223], v194 offset:58368
	v_mfma_f32_16x16x32_bf16 v[96:99], v[136:139], v[148:151], v[96:99]
	v_mfma_f32_16x16x32_bf16 v[88:91], v[128:131], v[148:151], v[88:91]
	ds_read_b128 v[224:227], v191 offset:32768
	v_mfma_f32_16x16x32_bf16 v[80:83], v[136:139], v[152:155], v[80:83]
	v_mfma_f32_16x16x32_bf16 v[72:75], v[128:131], v[152:155], v[72:75]
	ds_read_b128 v[228:231], v191 offset:33792
	v_mfma_f32_16x16x32_bf16 v[84:87], v[140:143], v[204:207], v[84:87]
	v_mfma_f32_16x16x32_bf16 v[76:79], v[144:147], v[204:207], v[76:79]
	ds_read_b128 v[232:235], v191 offset:34816
	v_mfma_f32_16x16x32_bf16 v[68:71], v[136:139], v[204:207], v[68:71]
	v_mfma_f32_16x16x32_bf16 v[56:59], v[128:131], v[204:207], v[56:59]
	ds_read_b128 v[236:239], v191 offset:35840
	s_waitcnt lgkmcnt(8)
	v_mfma_f32_16x16x32_bf16 v[36:39], v[140:143], v[156:159], v[36:39]
	v_mfma_f32_16x16x32_bf16 v[24:27], v[144:147], v[156:159], v[24:27]
	v_mfma_f32_16x16x32_bf16 v[4:7], v[140:143], v[240:243], v[4:7]
	v_mfma_f32_16x16x32_bf16 v[0:3], v[144:147], v[240:243], v[0:3]
	v_mfma_f32_16x16x32_bf16 v[32:35], v[140:143], v[244:247], v[32:35]
	v_mfma_f32_16x16x32_bf16 v[28:31], v[144:147], v[244:247], v[28:31]
	v_mfma_f32_16x16x32_bf16 v[12:15], v[140:143], v[248:251], v[12:15]
	v_mfma_f32_16x16x32_bf16 v[8:11], v[144:147], v[248:251], v[8:11]
	v_mfma_f32_16x16x32_bf16 v[64:67], v[136:139], v[156:159], v[64:67]
	v_mfma_f32_16x16x32_bf16 v[60:63], v[128:131], v[156:159], v[60:63]
	v_mfma_f32_16x16x32_bf16 v[52:55], v[136:139], v[240:243], v[52:55]
	v_mfma_f32_16x16x32_bf16 v[48:51], v[128:131], v[240:243], v[48:51]
	v_mfma_f32_16x16x32_bf16 v[44:47], v[136:139], v[244:247], v[44:47]
	v_mfma_f32_16x16x32_bf16 v[40:43], v[128:131], v[244:247], v[40:43]
	v_mfma_f32_16x16x32_bf16 v[20:23], v[136:139], v[248:251], v[20:23]
	v_mfma_f32_16x16x32_bf16 v[16:19], v[128:131], v[248:251], v[16:19]
	s_waitcnt vmcnt(4)
	s_barrier
	s_cmp_ge_u32 s28, 28
	s_cbranch_scc1 .Lg0_nost_1
	s_mov_b32 m0, s29
	s_add_u32 s18, s98, 0x40000
	s_addc_u32 s19, s99, 0
	global_load_lds_dwordx4 v160, s[98:99]
	s_add_u32 m0, s29, 0x4000
	s_add_u32 s16, s100, 0x40000
	s_addc_u32 s17, s101, 0
	global_load_lds_dwordx4 v160, s[100:101]
	s_add_u32 m0, s29, 0x2000
	s_add_u32 s98, s98, 0x2000
	s_addc_u32 s99, s99, 0
	global_load_lds_dwordx4 v160, s[18:19]
	s_add_u32 m0, s29, 0x6000
	s_add_u32 s100, s100, 0x2000
	s_addc_u32 s101, s101, 0
	global_load_lds_dwordx4 v160, s[16:17]
.Lg0_nost_1:
	ds_read_b128 v[156:159], v191 offset:40960
	ds_read_b128 v[240:243], v191 offset:41984
	ds_read_b128 v[244:247], v191 offset:43008
	ds_read_b128 v[248:251], v191 offset:44032
	s_waitcnt lgkmcnt(4)
	v_mfma_f32_16x16x32_bf16 v[124:127], v[208:211], v[224:227], v[124:127]
	v_mfma_f32_16x16x32_bf16 v[120:123], v[212:215], v[224:227], v[120:123]
	ds_read_b128 v[140:143], v202 offset:16384
	v_mfma_f32_16x16x32_bf16 v[116:119], v[208:211], v[228:231], v[116:119]
	v_mfma_f32_16x16x32_bf16 v[108:111], v[212:215], v[228:231], v[108:111]
	ds_read_b128 v[144:147], v202 offset:17408
	v_mfma_f32_16x16x32_bf16 v[100:103], v[208:211], v[232:235], v[100:103]
	v_mfma_f32_16x16x32_bf16 v[92:95], v[212:215], v[232:235], v[92:95]
	ds_read_b128 v[136:139], v202 offset:24576
	v_mfma_f32_16x16x32_bf16 v[112:115], v[216:219], v[224:227], v[112:115]
	v_mfma_f32_16x16x32_bf16 v[104:107], v[220:223], v[224:227], v[104:107]
	ds_read_b128 v[128:131], v202 offset:25600
	v_mfma_f32_16x16x32_bf16 v[96:99], v[216:219], v[228:231], v[96:99]
	v_mfma_f32_16x16x32_bf16 v[88:91], v[220:223], v[228:231], v[88:91]
	ds_read_b128 v[132:135], v192
	v_mfma_f32_16x16x32_bf16 v[80:83], v[216:219], v[232:235], v[80:83]
	v_mfma_f32_16x16x32_bf16 v[72:75], v[220:223], v[232:235], v[72:75]
	ds_read_b128 v[148:151], v192 offset:1024
	v_mfma_f32_16x16x32_bf16 v[84:87], v[208:211], v[236:239], v[84:87]
	v_mfma_f32_16x16x32_bf16 v[76:79], v[212:215], v[236:239], v[76:79]
	ds_read_b128 v[152:155], v192 offset:2048
	v_mfma_f32_16x16x32_bf16 v[68:71], v[216:219], v[236:239], v[68:71]
	v_mfma_f32_16x16x32_bf16 v[56:59], v[220:223], v[236:239], v[56:59]
	ds_read_b128 v[204:207], v192 offset:3072
	s_waitcnt lgkmcnt(8)
	v_mfma_f32_16x16x32_bf16 v[36:39], v[208:211], v[156:159], v[36:39]
	v_mfma_f32_16x16x32_bf16 v[24:27], v[212:215], v[156:159], v[24:27]
	v_mfma_f32_16x16x32_bf16 v[4:7], v[208:211], v[240:243], v[4:7]
	v_mfma_f32_16x16x32_bf16 v[0:3], v[212:215], v[240:243], v[0:3]
	v_mfma_f32_16x16x32_bf16 v[32:35], v[208:211], v[244:247], v[32:35]
	v_mfma_f32_16x16x32_bf16 v[28:31], v[212:215], v[244:247], v[28:31]
	v_mfma_f32_16x16x32_bf16 v[12:15], v[208:211], v[248:251], v[12:15]
	v_mfma_f32_16x16x32_bf16 v[8:11], v[212:215], v[248:251], v[8:11]
	v_mfma_f32_16x16x32_bf16 v[64:67], v[216:219], v[156:159], v[64:67]
	v_mfma_f32_16x16x32_bf16 v[60:63], v[220:223], v[156:159], v[60:63]
	v_mfma_f32_16x16x32_bf16 v[52:55], v[216:219], v[240:243], v[52:55]
	v_mfma_f32_16x16x32_bf16 v[48:51], v[220:223], v[240:243], v[48:51]
	v_mfma_f32_16x16x32_bf16 v[44:47], v[216:219], v[244:247], v[44:47]
	v_mfma_f32_16x16x32_bf16 v[40:43], v[220:223], v[244:247], v[40:43]
	v_mfma_f32_16x16x32_bf16 v[20:23], v[216:219], v[248:251], v[20:23]
	v_mfma_f32_16x16x32_bf16 v[16:19], v[220:223], v[248:251], v[16:19]
	s_cmp_lt_u32 s28, 28
	s_cbranch_scc1 .Lg0_w4_2
	s_waitcnt vmcnt(0)
; #define WAIT_V(n) asm volatile("s_waitcnt vmcnt(" #n ")" ::: "memory")
; #define BAR __builtin_amdgcn_s_barrier()
; #define LDA_(dst, ai) _Pragma("unroll") for (int m = 0; m < 4; ++m) dst[m] = *(const bf16x8*)(sb + (ai) * 8192 + la0 + m * 1024)
; #define LDB_(dst) _Pragma("unroll") for (int bj = 0; bj < 2; ++bj) _Pragma("unroll") for (int n = 0; n < 2; ++n) dst[bj][n] = *(const bf16x8*)(sb + 16384 + bj * 8192 + lb0 + n * 1024)
; #define MMA_(ai, bf_, af_) _Pragma("unroll") for (int bj = 0; bj < 2; ++bj) _Pragma("unroll") for (int m = 0; m < 4; ++m) _Pragma("unroll") for (int n = 0; n < 2; ++n) \
;         acc[ai][bj][m][n] = __builtin_amdgcn_mfma_f32_16x16x32_bf16(bf_[bj][n], af_[m], acc[ai][bj][m][n], 0, 0, 0)
; template <int MODE>
; DI void gemm_phase(const Params& p, int layer, int hf, unsigned char* shmc, int tid) {
;     ...
;     for (int kt = 0; kt < nt; ++kt) {
;       const int rem = nt - 1 - kt;
;       if (rem >= 2) WAIT_V(8); else if (rem == 1) WAIT_V(4); else WAIT_V(0);
;       BAR;
;       const unsigned char* sb = shmc + (kt & 3) * 32768;
;     ...
;       {
;         bf16x8 b0[2][2], a0[4], a1[4];
;         LDB_(b0); LDA_(a0, 0);
;         __builtin_amdgcn_sched_barrier(0);
;         LDA_(a1, 1); MMA_(0, b0, a0);
;         __builtin_amdgcn_sched_barrier(0);
;         if (kt + 3 < nt) STAGE_ALL((kt + 3) & 3, kt + 3);
;         __builtin_amdgcn_sched_barrier(0);
;         MMA_(1, b0, a1);
;       }
.Lg0_w4_2:
	s_waitcnt vmcnt(4)
	s_barrier
	s_cmp_ge_u32 s28, 28
	s_cbranch_scc1 .Lg0_nost_2
	s_add_u32 m0, s29, 0x8000
	s_add_u32 s18, s98, 0x40000
	s_addc_u32 s19, s99, 0
	global_load_lds_dwordx4 v160, s[98:99]
	s_add_u32 m0, s29, 0xc000
	s_add_u32 s16, s100, 0x40000
	s_addc_u32 s17, s101, 0
	global_load_lds_dwordx4 v160, s[100:101]
	s_add_u32 m0, s29, 0xa000
	s_add_u32 s98, s98, 0x2000
	s_addc_u32 s99, s99, 0
	global_load_lds_dwordx4 v160, s[18:19]
	s_add_u32 m0, s29, 0xe000
	s_add_u32 s100, s100, 0x2000
	s_addc_u32 s101, s101, 0
	global_load_lds_dwordx4 v160, s[16:17]
.Lg0_nost_2:
	ds_read_b128 v[156:159], v192 offset:8192
	ds_read_b128 v[240:243], v192 offset:9216
	ds_read_b128 v[244:247], v192 offset:10240
	ds_read_b128 v[248:251], v192 offset:11264
	s_waitcnt lgkmcnt(4)
	v_mfma_f32_16x16x32_bf16 v[124:127], v[140:143], v[132:135], v[124:127]
	v_mfma_f32_16x16x32_bf16 v[120:123], v[144:147], v[132:135], v[120:123]
	ds_read_b128 v[208:211], v202 offset:49152
	v_mfma_f32_16x16x32_bf16 v[116:119], v[140:143], v[148:151], v[116:119]
	v_mfma_f32_16x16x32_bf16 v[108:111], v[144:147], v[148:151], v[108:111]
	ds_read_b128 v[212:215], v202 offset:50176
	v_mfma_f32_16x16x32_bf16 v[100:103], v[140:143], v[152:155], v[100:103]
	v_mfma_f32_16x16x32_bf16 v[92:95], v[144:147], v[152:155], v[92:95]
	ds_read_b128 v[216:219], v202 offset:57344
	v_mfma_f32_16x16x32_bf16 v[112:115], v[136:139], v[132:135], v[112:115]
	v_mfma_f32_16x16x32_bf16 v[104:107], v[128:131], v[132:135], v[104:107]
	ds_read_b128 v[220:223], v202 offset:58368
	v_mfma_f32_16x16x32_bf16 v[96:99], v[136:139], v[148:151], v[96:99]
	v_mfma_f32_16x16x32_bf16 v[88:91], v[128:131], v[148:151], v[88:91]
	ds_read_b128 v[224:227], v192 offset:32768
	v_mfma_f32_16x16x32_bf16 v[80:83], v[136:139], v[152:155], v[80:83]
	v_mfma_f32_16x16x32_bf16 v[72:75], v[128:131], v[152:155], v[72:75]
	ds_read_b128 v[228:231], v192 offset:33792
	v_mfma_f32_16x16x32_bf16 v[84:87], v[140:143], v[204:207], v[84:87]
	v_mfma_f32_16x16x32_bf16 v[76:79], v[144:147], v[204:207], v[76:79]
	ds_read_b128 v[232:235], v192 offset:34816
	v_mfma_f32_16x16x32_bf16 v[68:71], v[136:139], v[204:207], v[68:71]
	v_mfma_f32_16x16x32_bf16 v[56:59], v[128:131], v[204:207], v[56:59]
	ds_read_b128 v[236:239], v192 offset:35840
	s_waitcnt lgkmcnt(8)
	v_mfma_f32_16x16x32_bf16 v[36:39], v[140:143], v[156:159], v[36:39]
	v_mfma_f32_16x16x32_bf16 v[24:27], v[144:147], v[156:159], v[24:27]
	v_mfma_f32_16x16x32_bf16 v[4:7], v[140:143], v[240:243], v[4:7]
	v_mfma_f32_16x16x32_bf16 v[0:3], v[144:147], v[240:243], v[0:3]
	v_mfma_f32_16x16x32_bf16 v[32:35], v[140:143], v[244:247], v[32:35]
	v_mfma_f32_16x16x32_bf16 v[28:31], v[144:147], v[244:247], v[28:31]
	v_mfma_f32_16x16x32_bf16 v[12:15], v[140:143], v[248:251], v[12:15]
	v_mfma_f32_16x16x32_bf16 v[8:11], v[144:147], v[248:251], v[8:11]
	v_mfma_f32_16x16x32_bf16 v[64:67], v[136:139], v[156:159], v[64:67]
	v_mfma_f32_16x16x32_bf16 v[60:63], v[128:131], v[156:159], v[60:63]
	v_mfma_f32_16x16x32_bf16 v[52:55], v[136:139], v[240:243], v[52:55]
	v_mfma_f32_16x16x32_bf16 v[48:51], v[128:131], v[240:243], v[48:51]
	v_mfma_f32_16x16x32_bf16 v[44:47], v[136:139], v[244:247], v[44:47]
	v_mfma_f32_16x16x32_bf16 v[40:43], v[128:131], v[244:247], v[40:43]
	v_mfma_f32_16x16x32_bf16 v[20:23], v[136:139], v[248:251], v[20:23]
	v_mfma_f32_16x16x32_bf16 v[16:19], v[128:131], v[248:251], v[16:19]
	s_cmp_lt_u32 s28, 28
	s_cbranch_scc1 .Lg0_w4_3
	s_waitcnt vmcnt(0)
.Lg0_w4_3:
	s_waitcnt vmcnt(4)
	s_barrier
	s_cmp_ge_u32 s28, 28
	s_cbranch_scc1 .Lg0_nost_3
	s_add_u32 m0, s29, 0x10000
	s_add_u32 s18, s98, 0x40000
	s_addc_u32 s19, s99, 0
	global_load_lds_dwordx4 v160, s[98:99]
	s_add_u32 m0, s29, 0x14000
	s_add_u32 s16, s100, 0x40000
	s_addc_u32 s17, s101, 0
	global_load_lds_dwordx4 v160, s[100:101]
	s_add_u32 m0, s29, 0x12000
	s_add_u32 s98, s98, 0x2000
	s_addc_u32 s99, s99, 0
	global_load_lds_dwordx4 v160, s[18:19]
	s_add_u32 m0, s29, 0x16000
	s_add_u32 s100, s100, 0x2000
	s_addc_u32 s101, s101, 0
	global_load_lds_dwordx4 v160, s[16:17]
.Lg0_nost_3:
	ds_read_b128 v[156:159], v192 offset:40960
	ds_read_b128 v[240:243], v192 offset:41984
	ds_read_b128 v[244:247], v192 offset:43008
	ds_read_b128 v[248:251], v192 offset:44032
	s_waitcnt lgkmcnt(4)
	v_mfma_f32_16x16x32_bf16 v[124:127], v[208:211], v[224:227], v[124:127]
	v_mfma_f32_16x16x32_bf16 v[120:123], v[212:215], v[224:227], v[120:123]
	ds_read_b128 v[140:143], v194 offset:16384
	v_mfma_f32_16x16x32_bf16 v[116:119], v[208:211], v[228:231], v[116:119]
	v_mfma_f32_16x16x32_bf16 v[108:111], v[212:215], v[228:231], v[108:111]
	ds_read_b128 v[144:147], v194 offset:17408
	v_mfma_f32_16x16x32_bf16 v[100:103], v[208:211], v[232:235], v[100:103]
	v_mfma_f32_16x16x32_bf16 v[92:95], v[212:215], v[232:235], v[92:95]
	ds_read_b128 v[136:139], v194 offset:24576
	v_mfma_f32_16x16x32_bf16 v[112:115], v[216:219], v[224:227], v[112:115]
	v_mfma_f32_16x16x32_bf16 v[104:107], v[220:223], v[224:227], v[104:107]
	ds_read_b128 v[128:131], v194 offset:25600
	v_mfma_f32_16x16x32_bf16 v[96:99], v[216:219], v[228:231], v[96:99]
	v_mfma_f32_16x16x32_bf16 v[88:91], v[220:223], v[228:231], v[88:91]
	ds_read_b128 v[132:135], v191
	v_mfma_f32_16x16x32_bf16 v[80:83], v[216:219], v[232:235], v[80:83]
	v_mfma_f32_16x16x32_bf16 v[72:75], v[220:223], v[232:235], v[72:75]
	ds_read_b128 v[148:151], v191 offset:1024
	v_mfma_f32_16x16x32_bf16 v[84:87], v[208:211], v[236:239], v[84:87]
	v_mfma_f32_16x16x32_bf16 v[76:79], v[212:215], v[236:239], v[76:79]
	ds_read_b128 v[152:155], v191 offset:2048
	v_mfma_f32_16x16x32_bf16 v[68:71], v[216:219], v[236:239], v[68:71]
	v_mfma_f32_16x16x32_bf16 v[56:59], v[220:223], v[236:239], v[56:59]
	ds_read_b128 v[204:207], v191 offset:3072
	s_waitcnt lgkmcnt(8)
	v_mfma_f32_16x16x32_bf16 v[36:39], v[208:211], v[156:159], v[36:39]
	v_mfma_f32_16x16x32_bf16 v[24:27], v[212:215], v[156:159], v[24:27]
	v_mfma_f32_16x16x32_bf16 v[4:7], v[208:211], v[240:243], v[4:7]
	v_mfma_f32_16x16x32_bf16 v[0:3], v[212:215], v[240:243], v[0:3]
	v_mfma_f32_16x16x32_bf16 v[32:35], v[208:211], v[244:247], v[32:35]
	v_mfma_f32_16x16x32_bf16 v[28:31], v[212:215], v[244:247], v[28:31]
	v_mfma_f32_16x16x32_bf16 v[12:15], v[208:211], v[248:251], v[12:15]
	v_mfma_f32_16x16x32_bf16 v[8:11], v[212:215], v[248:251], v[8:11]
	v_mfma_f32_16x16x32_bf16 v[64:67], v[216:219], v[156:159], v[64:67]
	v_mfma_f32_16x16x32_bf16 v[60:63], v[220:223], v[156:159], v[60:63]
	v_mfma_f32_16x16x32_bf16 v[52:55], v[216:219], v[240:243], v[52:55]
	v_mfma_f32_16x16x32_bf16 v[48:51], v[220:223], v[240:243], v[48:51]
	v_mfma_f32_16x16x32_bf16 v[44:47], v[216:219], v[244:247], v[44:47]
	v_mfma_f32_16x16x32_bf16 v[40:43], v[220:223], v[244:247], v[40:43]
	v_mfma_f32_16x16x32_bf16 v[20:23], v[216:219], v[248:251], v[20:23]
	v_mfma_f32_16x16x32_bf16 v[16:19], v[220:223], v[248:251], v[16:19]
	s_add_i32 s28, s28, 4
	s_cmp_lt_u32 s28, 32
	s_cbranch_scc1 .Lg0_loop
	s_waitcnt lgkmcnt(0)
